# deferred transpose hooks in the QKV and MoE up-projection phases claim 12 units
# baseline (speedup 1.0000x reference)
; __device__ __forceinline__ int get_bid() { int b = blockIdx.x; asm volatile("" : "+s"(b)); return b; }
; __device__ __forceinline__ void deferred_work(const Params& P, LAS unsigned char* lds, int maxclaims, int units, int limit_items) {
;     ...
;     for (int n = 0; n < maxclaims; ++n) {
;         __syncthreads();
;         if (tid == 0) { int c = -1; const unsigned cur = __hip_atomic_load(ctr, __ATOMIC_RELAXED, __HIP_MEMORY_SCOPE_AGENT);
;             const int stop = limit_items > 0 ? limit_items : TR_DEF;
;             if ((int)cur * DCH < stop) c = (int)atomicAdd(ctr, (unsigned)units);
;             *sc = c; }
;         __syncthreads();
; __global__ void __launch_bounds__(NTHR, 2) mega_fwd(Params P) {
;     ...
;                 if (DEFER && DEFER_HOOKS && rep == 0 && ph == 15) { const int rem = (S.T * S.nN) % (int)gridDim.x; if (rem != 0 && get_bid() >= rem) deferred_work(P, lds, 1, 3, 0); } } break;
.LBB0_520:
	v_readlane_b32 s0, v253, 22
	v_readlane_b32 s1, v253, 23
	v_readlane_b32 s52, v253, 11
	v_readlane_b32 s70, v253, 15
	v_readlane_b32 s60, v253, 19
	s_andn2_b64 vcc, exec, s[0:1]
	v_readlane_b32 s83, v253, 4
	v_readlane_b32 s84, v253, 5
	v_readlane_b32 s53, v253, 12
	v_readlane_b32 s71, v253, 16
	v_readlane_b32 s61, v253, 20
	s_mov_b32 s95, 0x92492493
	s_movk_i32 s48, 0x7000
	s_cbranch_vccnz .LBB0_561
	s_waitcnt lgkmcnt(0)
	s_abs_i32 s0, s79
	v_cvt_f32_u32_e32 v0, s0
	s_sub_i32 s3, 0, s0
	s_abs_i32 s2, s78
	s_ashr_i32 s1, s78, 31
	v_rcp_iflag_f32_e32 v0, v0
	s_nop 0
	v_mul_f32_e32 v0, 0x4f7ffffe, v0
	v_cvt_u32_f32_e32 v0, v0
	s_nop 0
	v_readfirstlane_b32 s4, v0
	s_mul_i32 s3, s3, s4
	s_mul_hi_u32 s3, s4, s3
	s_add_i32 s4, s4, s3
	s_mul_hi_u32 s3, s2, s4
	s_mul_i32 s3, s3, s0
	s_sub_i32 s2, s2, s3
	s_sub_i32 s3, s2, s0
	s_cmp_ge_u32 s2, s0
	s_cselect_b32 s2, s3, s2
	s_sub_i32 s3, s2, s0
	s_cmp_ge_u32 s2, s0
	s_cselect_b32 s0, s3, s2
	s_xor_b32 s0, s0, s1
	s_sub_i32 s0, s0, s1
	s_cmp_eq_u32 s0, 0
	s_cbranch_scc1 .LBB0_561
	s_mov_b32 s1, s74
	s_cmp_lt_i32 s1, s0
	s_cbranch_scc1 .LBB0_561
	v_mov_b32_e32 v14, v196
	s_waitcnt vmcnt(0)
	v_cmp_eq_u32_e32 vcc, 0, v14
	s_barrier
	s_and_saveexec_b64 s[0:1], vcc
	v_readlane_b32 s10, v253, 9
	v_readlane_b32 s11, v253, 10
	s_cbranch_execz .LBB0_529
	s_nop 3
	global_load_dword v2, v1, s[10:11] sc1
	s_movk_i32 s2, 0x179f
	v_mov_b32_e32 v0, -1
	s_waitcnt vmcnt(0)
	v_cmp_lt_i32_e32 vcc, s2, v2
	s_cbranch_vccnz .LBB0_528
	s_mov_b64 s[6:7], exec
	v_mbcnt_lo_u32_b32 v0, s6, 0
	v_mbcnt_hi_u32_b32 v0, s7, v0
	v_cmp_eq_u32_e32 vcc, 0, v0
	s_and_saveexec_b64 s[4:5], vcc
	s_cbranch_execz .LBB0_527
	s_bcnt1_i32_b64 s2, s[6:7]
	s_mul_i32 s2, s2, 12
	v_mov_b32_e32 v2, s2
	global_atomic_add v2, v1, v2, s[10:11] sc0
.LBB0_527:
	s_or_b64 exec, exec, s[4:5]
	s_waitcnt vmcnt(0)
	v_readfirstlane_b32 s2, v2
	s_nop 1
	v_mad_u32_u24 v0, v0, 12, s2

; __device__ __forceinline__ TDesc tr_decode(const Params& P, unsigned char* ws, int it, int deferred) {
;     int r = it;
;     if (deferred) {
;         if (r < TR_WI) return tr_mk(P.ffn_wi + (size_t)1024 * 7168, 1024, 7168, (bf16_t*)(ws + O_FWI) + (size_t)7168 * 1024, 1, r); r -= TR_WI;
;         if (r < TR_WO) return tr_mk(P.ffn_wo + (size_t)3584 * 1024, 3584, 1024, (bf16_t*)(ws + O_FWO) + (size_t)1024 * 3584, 0, r); r -= TR_WO;
;         if (r < 8 * TR_WI) { const int e = 8 + r / TR_WI; return tr_mk(P.moe_wi + (size_t)e * 1024 * 7168, 1024, 7168, (bf16_t*)(ws + O_MWI) + (size_t)e * 7168 * 1024, 1, r % TR_WI); } r -= 8 * TR_WI;
;         { const int e = 8 + r / TR_WO; return tr_mk(P.moe_wo + (size_t)e * 3584 * 1024, 3584, 1024, (bf16_t*)(ws + O_MWO) + (size_t)e * 1024 * 3584, 0, r % TR_WO); }
; __device__ __forceinline__ void deferred_work(const Params& P, LAS unsigned char* lds, int maxclaims, int units, int limit_items) {
;     ...
;         const int c = *sc, base = c * DCH;
;         if (c < 0 || base >= TR_DEF) break;
;         const int cend = base + units * DCH, i1 = cend < TR_DEF ? cend : TR_DEF;
;         int it = base + wave;
;         float v[32]; TDesc cur;
;         if (it < i1) { cur = tr_decode(P, ws, it, 1); tr_load(cur, v, lane); }
;         while (it < i1) {
;             const int nit = it + NWAVE; float w[32]; TDesc nx = cur;
;             if (nit < i1) { nx = tr_decode(P, ws, nit, 1); tr_load(nx, w, lane); }
.LBB0_529:
	s_or_b64 exec, exec, s[0:1]
	v_lshlrev_b32_e32 v0, 3, v14
	v_and_b32_e32 v18, 56, v0
	v_mov_b32_e32 v0, s69
	s_waitcnt lgkmcnt(0)
	s_barrier
	ds_read_b32 v0, v0
	s_movk_i32 s0, 0x179f
	v_bfe_u32 v9, v14, 5, 1
	v_and_b32_e32 v8, 63, v14
	v_mul_u32_u24_e32 v15, 0x84, v9
	s_waitcnt lgkmcnt(0)
	v_cmp_lt_u32_e32 vcc, s0, v0
	v_mul_u32_u24_e32 v10, 0x84, v18
	s_cbranch_vccnz .LBB0_560
	v_lshlrev_b32_e32 v0, 3, v0
	v_ashrrev_i32_e32 v12, 6, v14
	v_min_u32_e32 v2, 0xbca0, v0
	v_add_u32_e32 v11, 0x60, v2
	v_add_u32_e32 v16, v0, v12
	v_cmp_lt_i32_e32 vcc, v16, v11
	s_and_saveexec_b64 s[4:5], vcc
	s_cbranch_execz .LBB0_559
	s_movk_i32 s0, 0xdff
	v_cmp_lt_i32_e32 vcc, s0, v16
	s_and_saveexec_b64 s[0:1], vcc
	s_xor_b64 s[0:1], exec, s[0:1]
	s_cbranch_execz .LBB0_541
	v_cmp_lt_u32_e32 vcc, s62, v16
	s_and_saveexec_b64 s[6:7], vcc
	s_xor_b64 s[6:7], exec, s[6:7]
	s_cbranch_execz .LBB0_538
	s_mov_b32 s2, 0x84ff
	v_cmp_lt_u32_e32 vcc, s2, v16
	s_and_saveexec_b64 s[8:9], vcc
	s_xor_b64 s[8:9], exec, s[8:9]
	s_cbranch_execz .LBB0_535
	v_add_u16_e32 v0, 0x7b00, v16
	s_movk_i32 s2, 0x2493
	v_mul_u32_u24_sdwa v13, v0, s2 dst_sel:DWORD dst_unused:UNUSED_PAD src0_sel:BYTE_1 src1_sel:DWORD
	v_add_u16_sdwa v6, v13, v201 dst_sel:DWORD dst_unused:UNUSED_PAD src0_sel:WORD_1 src1_sel:DWORD
	v_mov_b64_e32 v[2:3], s[24:25]
	s_mov_b32 s2, 0xe00000
	v_mad_u64_u32 v[2:3], s[10:11], v6, s2, v[2:3]
	v_mov_b64_e32 v[4:5], s[52:53]
	s_mov_b32 s2, 0x700000
	v_mad_u64_u32 v[6:7], s[10:11], v6, s2, v[4:5]
	s_movk_i32 s2, 0x700
	v_mul_lo_u16_sdwa v4, v13, s2 dst_sel:DWORD dst_unused:UNUSED_PAD src0_sel:WORD_1 src1_sel:DWORD
	v_sub_u16_e32 v0, v0, v4
	v_lshlrev_b16_e32 v4, 5, v0
	v_lshlrev_b16_e32 v0, 1, v0
	v_and_b32_e32 v4, 0x3e0, v4
	v_and_b32_e32 v13, 0xfc0, v0
	v_lshlrev_b32_sdwa v0, v202, v13 dst_sel:DWORD dst_unused:UNUSED_PAD src0_sel:DWORD src1_sel:WORD_0
	v_and_b32_e32 v17, 0xffff, v4
	v_lshl_add_u64 v[2:3], v[2:3], 0, v[0:1]
	v_lshlrev_b32_e32 v0, 2, v17
	s_movk_i32 s2, 0x1c00
	v_lshl_add_u64 v[4:5], v[2:3], 0, v[0:1]
	v_mad_u64_u32 v[2:3], s[10:11], v17, s2, v[6:7]
	v_lshlrev_b32_sdwa v0, v200, v13 dst_sel:DWORD dst_unused:UNUSED_PAD src0_sel:DWORD src1_sel:WORD_0
	v_lshl_add_u64 v[2:3], v[2:3], 0, v[0:1]

; __device__ __forceinline__ int get_bid() { int b = blockIdx.x; asm volatile("" : "+s"(b)); return b; }
; __device__ __forceinline__ void deferred_work(const Params& P, LAS unsigned char* lds, int maxclaims, int units, int limit_items) {
;     ...
;     for (int n = 0; n < maxclaims; ++n) {
;         __syncthreads();
;         if (tid == 0) { int c = -1; const unsigned cur = __hip_atomic_load(ctr, __ATOMIC_RELAXED, __HIP_MEMORY_SCOPE_AGENT);
;             const int stop = limit_items > 0 ? limit_items : TR_DEF;
;             if ((int)cur * DCH < stop) c = (int)atomicAdd(ctr, (unsigned)units);
;             *sc = c; }
;         __syncthreads();
; __global__ void __launch_bounds__(NTHR, 2) mega_fwd(Params P) {
;     ...
;                 if (DEFER && DEFER_HOOKS && rep == 0 && a0 == 1) { const int b = get_bid(); if (b >= 69 && !(b >= 128 && b < 193)) deferred_work(P, lds, 1, 3, 0); } } break;
.LBB0_766:
	v_readlane_b32 s0, v253, 40
	v_readlane_b32 s1, v253, 41
	s_andn2_b64 vcc, exec, s[0:1]
	s_cbranch_vccnz .LBB0_806
	s_mov_b32 s2, s74
	s_cmpk_lt_i32 s2, 0x45
	s_cselect_b64 s[0:1], -1, 0
	s_addk_i32 s2, 0xff80
	s_cmpk_lt_u32 s2, 0x41
	s_cselect_b64 s[4:5], -1, 0
	s_or_b64 s[0:1], s[0:1], s[4:5]
	s_and_b64 vcc, exec, s[0:1]
	s_cbranch_vccnz .LBB0_806
	v_mov_b32_e32 v14, v196
	s_waitcnt vmcnt(0) lgkmcnt(0)
	v_cmp_eq_u32_e32 vcc, 0, v14
	s_barrier
	s_and_saveexec_b64 s[0:1], vcc
	s_cbranch_execz .LBB0_774
	global_load_dword v2, v1, s[72:73] sc1
	s_movk_i32 s2, 0x179f
	v_mov_b32_e32 v0, -1
	s_waitcnt vmcnt(0)
	v_cmp_lt_i32_e32 vcc, s2, v2
	s_cbranch_vccnz .LBB0_773
	s_mov_b64 s[6:7], exec
	v_mbcnt_lo_u32_b32 v0, s6, 0
	v_mbcnt_hi_u32_b32 v0, s7, v0
	v_cmp_eq_u32_e32 vcc, 0, v0
	s_and_saveexec_b64 s[4:5], vcc
	s_cbranch_execz .LBB0_772
	s_bcnt1_i32_b64 s2, s[6:7]
	s_mul_i32 s2, s2, 12
	v_mov_b32_e32 v2, s2
	global_atomic_add v2, v1, v2, s[72:73] sc0
